# adds first-iteration peel of the S5 state GEMM K-loop
# baseline (speedup 1.0000x reference)
;     __device__ __forceinline__ const char* tile(const Unit& u, int t) const { return A + (size_t)u.pm * 2 * hstep() + (size_t)t * (BK * 2); }
;     __device__ __forceinline__ const char* tile(const Unit& u, int t) const { return U + (long)(t >> 2) * xoff + (size_t)u.pn * (1024 * 512) + (size_t)u.pm * 2 * hstep() + (size_t)(t & 3) * (BK * 2); }
; #define PG8_STAGE(bufoff, gbase, voff) do { _Pragma("unroll") for (int _i = 0; _i < 2; ++_i) \
;         __builtin_amdgcn_global_load_lds((const unsigned*)((const char*)(gbase) + (voff)[_i]), (PG8_LAS unsigned*)(lds + (bufoff) + ldsw + _i * 8192), 16, 0, 0); } while (0)
; #define PG8_LDA(dst, b, h) do { _Pragma("unroll") for (int m = 0; m < 4; ++m) _Pragma("unroll") for (int k = 0; k < 2; ++k) dst[m][k] = *(const PG8_LAS bf16x8*)(lds + PG8_SA(b, h) + aoff + m * 2048 + k * 1024); } while (0)
; #define PG8_LDB(dst, b, h) do { _Pragma("unroll") for (int n = 0; n < 2; ++n) _Pragma("unroll") for (int k = 0; k < 2; ++k) dst[n][k] = *(const PG8_LAS bf16x8*)(lds + PG8_SB(b, h) + boff + n * 2048 + k * 1024); } while (0)
; #define PG8_MMA(ai, bj, At, Bt) do { __builtin_amdgcn_s_setprio(1); _Pragma("unroll") for (int m = 0; m < 4; ++m) _Pragma("unroll") for (int n = 0; n < 2; ++n) _Pragma("unroll") for (int k = 0; k < 2; ++k) \
;         acc[ai][bj][m][n] = __builtin_amdgcn_mfma_f32_16x16x32_bf16(Bt[n][k], At[m][k], acc[ai][bj][m][n], 0, 0, 0); __builtin_amdgcn_s_setprio(0); } while (0)
; #define PG8_WAIT_V(n) asm volatile("s_waitcnt vmcnt(" #n ")" ::: "memory")
;     ...
;     for (;;) {
;         const bool has_next = S.next(ui + 1, nxt);
;         const Unit nu = has_next ? nxt : cur;
;         const char* nB = (const char*)g.Bt + (size_t)nu.pn * 2 * hstepB;
; #pragma unroll 1
;         for (int t = 0; t < nt; t += 2) {
;             const bool last = (t == nt - 2);
;             const char* a1 = AS.tile(cur, t + 1);
;             const char* a2 = last ? AS.tile(nu, 0) : AS.tile(cur, t + 2); const char* b2 = last ? nB : cB + (size_t)(t + 2) * kstep;
;             const char* a3 = last ? AS.tile(nu, 1) : AS.tile(cur, t + 3); const char* b3 = b2 + kstep;
;             PG8_LDB(B0, 0, 0); PG8_LDB(B1, 0, 1); PG8_SCHED; PG8_LDA(At, 0, 0); PG8_STAGE(PG8_SA(1, 1), a1 + hstepA, voffA);
;             PG8_WAIT_V(8); PG8_WAIT_L(0); PG8_BAR; PG8_MMA(0, 0, At, B0); PG8_MMA(0, 1, At, B1); PG8_BAR; PG8_SCHED;
.LBB0_784:
	s_and_b64 s[6:7], s[38:39], exec
	s_cselect_b32 s16, s43, s10
	s_cselect_b32 s15, s44, s8
	s_ashr_i32 s17, s16, 31
	s_lshl_b64 s[6:7], s[16:17], 17
	s_add_u32 s45, s28, s6
	s_addc_u32 s46, s29, s7
	s_ashr_i32 s11, s10, 31
	s_lshl_b64 s[10:11], s[10:11], 19
	v_readlane_b32 s21, v254, 37
	s_add_u32 s14, s21, s10
	v_readlane_b32 s22, v254, 38
	s_addc_u32 s20, s22, s11
	s_ashr_i32 s9, s8, 31
	s_lshl_b64 s[18:19], s[8:9], 17
	s_add_u32 s9, s14, s18
	s_addc_u32 s47, s20, s19
	s_lshl_b64 s[16:17], s[16:17], 19
	s_add_u32 s18, s21, s16
	s_mov_b32 s14, 0
	s_addc_u32 s19, s22, s17
	s_ashr_i64 s[16:17], s[14:15], 15
	s_add_u32 s48, s18, s16
	s_addc_u32 s49, s19, s17
	s_add_u32 s50, s48, 0x80
	s_addc_u32 s51, s49, 0
	s_add_u32 s52, s28, s12
	s_addc_u32 s53, s29, s13
	s_mov_b64 s[12:13], -1
	s_mov_b64 s[16:17], 0
	s_mov_b64 s[66:67], 0x80
.Lpeel_785:
	s_add_u32 s24, s9, s14
	s_addc_u32 s25, s47, 0
	s_xor_b32 s15, s14, 0x100
	s_add_u32 s15, s9, s15
	s_addc_u32 s20, s47, 0
	s_and_b64 s[18:19], s[16:17], exec
	s_cselect_b32 s21, s49, s20
	s_cselect_b32 s20, s48, s15
	s_add_u32 s15, s52, s14
	s_addc_u32 s18, s53, 0
	s_add_u32 s15, s15, 0x100
	s_addc_u32 s22, s18, 0
	s_and_b64 s[18:19], s[16:17], exec
	s_cselect_b32 s23, s46, s22
	s_cselect_b32 s22, s45, s15
	s_addk_i32 s14, 0x180
	s_and_b32 s14, s14, 0x180
	s_add_u32 s18, s9, s14
	s_addc_u32 s19, s47, 0
	s_and_b64 s[14:15], s[16:17], exec
	s_cselect_b32 s14, s50, s18
	s_cselect_b32 s15, s51, s19
	s_add_i32 s17, 0, 0x10000
	s_add_i32 s62, 0, 0x14000
	s_add_u32 s26, s24, 0x10080
	s_addc_u32 s27, s25, 0
	s_add_i32 s61, s17, s30
	s_add_i32 m0, s31, 0xc000
	s_add_i32 s64, s31, 0xe000
	s_add_i32 s58, s61, 0x2000
	v_add_u32_e32 v140, s17, v159
	s_add_u32 s24, s22, 0x10000
	ds_read_b128 v[162:165], v140
	ds_read_b128 v[166:169], v140 offset:1024
	ds_read_b128 v[170:173], v140 offset:2048
	ds_read_b128 v[174:177], v140 offset:3072
	v_add_u32_e32 v140, s62, v159
	s_addc_u32 s25, s23, 0
	s_add_i32 s60, s62, s30
	ds_read_b128 v[178:181], v140
	ds_read_b128 v[182:185], v140 offset:1024
	ds_read_b128 v[186:189], v140 offset:2048
	ds_read_b128 v[190:193], v140 offset:3072
	s_add_i32 s59, s60, 0x2000
	s_add_i32 s57, 0, 0x18000
	s_add_i32 s56, 0, 0x1c000
	s_add_u32 s18, s20, 0x10000
	s_addc_u32 s19, s21, 0
	s_add_i32 s55, s57, s30
	s_add_i32 s54, s55, 0x2000
	s_add_u32 s16, s22, 0x10080
	s_addc_u32 s17, s23, 0
	s_add_i32 s63, s56, s30
	s_add_i32 s62, s63, 0x2000
	v_lshl_add_u64 v[140:141], s[26:27], 0, v[128:129]
	ds_read_b128 v[194:197], v160
	ds_read_b128 v[198:201], v160 offset:1024
	ds_read_b128 v[202:205], v160 offset:2048
	ds_read_b128 v[218:221], v160 offset:3072
	ds_read_b128 v[222:225], v160 offset:4096
	ds_read_b128 v[238:241], v160 offset:5120
	ds_read_b128 v[242:245], v160 offset:6144
	ds_read_b128 v[246:249], v160 offset:7168
	global_load_lds_dwordx4 v[140:141], off
	v_lshl_add_u64 v[140:141], s[26:27], 0, v[130:131]
	s_mov_b32 m0, s64
	s_nop 0
	global_load_lds_dwordx4 v[140:141], off
	s_waitcnt vmcnt(8)
	s_waitcnt lgkmcnt(0)
	s_barrier
	s_setprio 1
	s_waitcnt lgkmcnt(0)
	v_mfma_f32_16x16x32_bf16 v[124:127], v[162:165], v[194:197], 0
	v_mfma_f32_16x16x32_bf16 v[120:123], v[170:173], v[194:197], 0
	v_mfma_f32_16x16x32_bf16 v[116:119], v[162:165], v[202:205], 0
	v_mfma_f32_16x16x32_bf16 v[108:111], v[170:173], v[202:205], 0
	v_mfma_f32_16x16x32_bf16 v[100:103], v[162:165], v[222:225], 0
	v_mfma_f32_16x16x32_bf16 v[92:95], v[170:173], v[222:225], 0
	v_mfma_f32_16x16x32_bf16 v[84:87], v[162:165], v[242:245], 0
	v_mfma_f32_16x16x32_bf16 v[76:79], v[170:173], v[242:245], 0
	v_mfma_f32_16x16x32_bf16 v[124:127], v[166:169], v[198:201], v[124:127]
	v_mfma_f32_16x16x32_bf16 v[120:123], v[174:177], v[198:201], v[120:123]
	v_mfma_f32_16x16x32_bf16 v[116:119], v[166:169], v[218:221], v[116:119]
	v_mfma_f32_16x16x32_bf16 v[108:111], v[174:177], v[218:221], v[108:111]
	v_mfma_f32_16x16x32_bf16 v[100:103], v[166:169], v[238:241], v[100:103]
	v_mfma_f32_16x16x32_bf16 v[92:95], v[174:177], v[238:241], v[92:95]
	v_mfma_f32_16x16x32_bf16 v[84:87], v[166:169], v[246:249], v[84:87]
	v_mfma_f32_16x16x32_bf16 v[76:79], v[174:177], v[246:249], v[76:79]
	s_setprio 0
	s_setprio 1
	v_mfma_f32_16x16x32_bf16 v[112:115], v[178:181], v[194:197], 0
	v_mfma_f32_16x16x32_bf16 v[104:107], v[186:189], v[194:197], 0
	v_mfma_f32_16x16x32_bf16 v[96:99], v[178:181], v[202:205], 0
	v_mfma_f32_16x16x32_bf16 v[88:91], v[186:189], v[202:205], 0
	v_mfma_f32_16x16x32_bf16 v[80:83], v[178:181], v[222:225], 0
	v_mfma_f32_16x16x32_bf16 v[72:75], v[186:189], v[222:225], 0
	v_mfma_f32_16x16x32_bf16 v[68:71], v[178:181], v[242:245], 0
	v_mfma_f32_16x16x32_bf16 v[64:67], v[186:189], v[242:245], 0
	v_mfma_f32_16x16x32_bf16 v[112:115], v[182:185], v[198:201], v[112:115]
	v_mfma_f32_16x16x32_bf16 v[104:107], v[190:193], v[198:201], v[104:107]
	v_mfma_f32_16x16x32_bf16 v[96:99], v[182:185], v[218:221], v[96:99]
	v_mfma_f32_16x16x32_bf16 v[88:91], v[190:193], v[218:221], v[88:91]
	v_mfma_f32_16x16x32_bf16 v[80:83], v[182:185], v[238:241], v[80:83]
	v_mfma_f32_16x16x32_bf16 v[72:75], v[190:193], v[238:241], v[72:75]
	v_mfma_f32_16x16x32_bf16 v[68:71], v[182:185], v[246:249], v[68:71]
	v_mfma_f32_16x16x32_bf16 v[64:67], v[190:193], v[246:249], v[64:67]
	s_setprio 0
	s_barrier
; #define PG8_STAGE(bufoff, gbase, voff) do { _Pragma("unroll") for (int _i = 0; _i < 2; ++_i) \
;         __builtin_amdgcn_global_load_lds((const unsigned*)((const char*)(gbase) + (voff)[_i]), (PG8_LAS unsigned*)(lds + (bufoff) + ldsw + _i * 8192), 16, 0, 0); } while (0)
; #define PG8_LDA(dst, b, h) do { _Pragma("unroll") for (int m = 0; m < 4; ++m) _Pragma("unroll") for (int k = 0; k < 2; ++k) dst[m][k] = *(const PG8_LAS bf16x8*)(lds + PG8_SA(b, h) + aoff + m * 2048 + k * 1024); } while (0)
; #define PG8_LDB(dst, b, h) do { _Pragma("unroll") for (int n = 0; n < 2; ++n) _Pragma("unroll") for (int k = 0; k < 2; ++k) dst[n][k] = *(const PG8_LAS bf16x8*)(lds + PG8_SB(b, h) + boff + n * 2048 + k * 1024); } while (0)
; #define PG8_MMA(ai, bj, At, Bt) do { __builtin_amdgcn_s_setprio(1); _Pragma("unroll") for (int m = 0; m < 4; ++m) _Pragma("unroll") for (int n = 0; n < 2; ++n) _Pragma("unroll") for (int k = 0; k < 2; ++k) \
;         acc[ai][bj][m][n] = __builtin_amdgcn_mfma_f32_16x16x32_bf16(Bt[n][k], At[m][k], acc[ai][bj][m][n], 0, 0, 0); __builtin_amdgcn_s_setprio(0); } while (0)
; #define PG8_WAIT_V(n) asm volatile("s_waitcnt vmcnt(" #n ")" ::: "memory")
; #define PG8_WAIT_L(n) asm volatile("s_waitcnt lgkmcnt(" #n ")" ::: "memory")
; #define PG8_BAR __builtin_amdgcn_s_barrier()
; #define PG8_SCHED __builtin_amdgcn_sched_barrier(0)
;     ...
;             PG8_LDA(At, 0, 1); PG8_STAGE(PG8_SB(0, 0), b2, voffB); PG8_STAGE(PG8_SB(0, 1), b2 + hstepB, voffB); PG8_STAGE(PG8_SA(0, 0), a2, voffA);
;             PG8_WAIT_V(8); PG8_WAIT_L(0); PG8_BAR; PG8_MMA(1, 0, At, B0); PG8_MMA(1, 1, At, B1); PG8_BAR; PG8_SCHED;
;             PG8_LDB(B0, 1, 0); PG8_LDB(B1, 1, 1); PG8_SCHED; PG8_LDA(At, 1, 0); PG8_STAGE(PG8_SA(0, 1), a2 + hstepA, voffA);
	s_mov_b32 m0, s61
	v_lshl_add_u64 v[140:141], s[22:23], 0, v[134:135]
	ds_read_b128 v[194:197], v160 offset:16384
	ds_read_b128 v[198:201], v160 offset:17408
	ds_read_b128 v[202:205], v160 offset:18432
	ds_read_b128 v[218:221], v160 offset:19456
	ds_read_b128 v[222:225], v160 offset:20480
	ds_read_b128 v[238:241], v160 offset:21504
	ds_read_b128 v[242:245], v160 offset:22528
	ds_read_b128 v[246:249], v160 offset:23552
	global_load_lds_dwordx4 v[140:141], off
	v_lshl_add_u64 v[206:207], s[22:23], 0, v[132:133]
	s_mov_b32 m0, s58
	v_lshl_add_u64 v[250:251], s[24:25], 0, v[134:135]
	global_load_lds_dwordx4 v[206:207], off
	s_mov_b32 m0, s60
	s_nop 0
	global_load_lds_dwordx4 v[250:251], off
	v_lshl_add_u64 v[250:251], s[24:25], 0, v[132:133]
	s_mov_b32 m0, s59
	s_nop 0
	global_load_lds_dwordx4 v[250:251], off
	v_lshl_add_u64 v[250:251], s[20:21], 0, v[128:129]
	s_mov_b32 m0, s31
	s_nop 0
	global_load_lds_dwordx4 v[250:251], off
	v_lshl_add_u64 v[250:251], s[20:21], 0, v[130:131]
	s_mov_b32 m0, s35
	s_nop 0
	global_load_lds_dwordx4 v[250:251], off
	s_waitcnt vmcnt(8)
	s_waitcnt lgkmcnt(0)
	s_barrier
	s_setprio 1
	s_waitcnt lgkmcnt(0)
	v_mfma_f32_16x16x32_bf16 v[60:63], v[162:165], v[194:197], 0
	v_mfma_f32_16x16x32_bf16 v[56:59], v[170:173], v[194:197], 0
	v_mfma_f32_16x16x32_bf16 v[52:55], v[162:165], v[202:205], 0
	v_mfma_f32_16x16x32_bf16 v[44:47], v[170:173], v[202:205], 0
	v_mfma_f32_16x16x32_bf16 v[36:39], v[162:165], v[222:225], 0
	v_mfma_f32_16x16x32_bf16 v[28:31], v[170:173], v[222:225], 0
	v_mfma_f32_16x16x32_bf16 v[20:23], v[162:165], v[242:245], 0
	v_mfma_f32_16x16x32_bf16 v[12:15], v[170:173], v[242:245], 0
	v_mfma_f32_16x16x32_bf16 v[60:63], v[166:169], v[198:201], v[60:63]
	v_mfma_f32_16x16x32_bf16 v[56:59], v[174:177], v[198:201], v[56:59]
	v_mfma_f32_16x16x32_bf16 v[52:55], v[166:169], v[218:221], v[52:55]
	v_mfma_f32_16x16x32_bf16 v[44:47], v[174:177], v[218:221], v[44:47]
	v_mfma_f32_16x16x32_bf16 v[36:39], v[166:169], v[238:241], v[36:39]
	v_mfma_f32_16x16x32_bf16 v[28:31], v[174:177], v[238:241], v[28:31]
	v_mfma_f32_16x16x32_bf16 v[20:23], v[166:169], v[246:249], v[20:23]
	v_mfma_f32_16x16x32_bf16 v[12:15], v[174:177], v[246:249], v[12:15]
	s_setprio 0
	s_setprio 1
	v_mfma_f32_16x16x32_bf16 v[48:51], v[178:181], v[194:197], 0
	v_mfma_f32_16x16x32_bf16 v[40:43], v[186:189], v[194:197], 0
	v_mfma_f32_16x16x32_bf16 v[32:35], v[178:181], v[202:205], 0
	v_mfma_f32_16x16x32_bf16 v[24:27], v[186:189], v[202:205], 0
	v_mfma_f32_16x16x32_bf16 v[16:19], v[178:181], v[222:225], 0
	v_mfma_f32_16x16x32_bf16 v[8:11], v[186:189], v[222:225], 0
	v_mfma_f32_16x16x32_bf16 v[4:7], v[178:181], v[242:245], 0
	v_mfma_f32_16x16x32_bf16 v[0:3], v[186:189], v[242:245], 0
	v_mfma_f32_16x16x32_bf16 v[48:51], v[182:185], v[198:201], v[48:51]
	v_mfma_f32_16x16x32_bf16 v[40:43], v[190:193], v[198:201], v[40:43]
	v_mfma_f32_16x16x32_bf16 v[32:35], v[182:185], v[218:221], v[32:35]
	v_mfma_f32_16x16x32_bf16 v[24:27], v[190:193], v[218:221], v[24:27]
	v_mfma_f32_16x16x32_bf16 v[16:19], v[182:185], v[238:241], v[16:19]
	v_mfma_f32_16x16x32_bf16 v[8:11], v[190:193], v[238:241], v[8:11]
	v_mfma_f32_16x16x32_bf16 v[4:7], v[182:185], v[246:249], v[4:7]
	v_mfma_f32_16x16x32_bf16 v[0:3], v[190:193], v[246:249], v[0:3]
	s_setprio 0
	s_barrier
	v_add_u32_e32 v161, s57, v159
	ds_read_b128 v[162:165], v161
	ds_read_b128 v[166:169], v161 offset:1024
	ds_read_b128 v[170:173], v161 offset:2048
	ds_read_b128 v[174:177], v161 offset:3072
	v_add_u32_e32 v161, s56, v159
	ds_read_b128 v[178:181], v161
	ds_read_b128 v[182:185], v161 offset:1024
	ds_read_b128 v[186:189], v161 offset:2048
	ds_read_b128 v[190:193], v161 offset:3072
	s_mov_b32 m0, s36
	v_lshl_add_u64 v[250:251], s[18:19], 0, v[128:129]
	ds_read_b128 v[194:197], v160 offset:32768
	ds_read_b128 v[198:201], v160 offset:33792
	ds_read_b128 v[202:205], v160 offset:34816
	ds_read_b128 v[218:221], v160 offset:35840
	ds_read_b128 v[222:225], v160 offset:36864
	ds_read_b128 v[238:241], v160 offset:37888
	ds_read_b128 v[242:245], v160 offset:38912
	ds_read_b128 v[246:249], v160 offset:39936
	global_load_lds_dwordx4 v[250:251], off
	v_lshl_add_u64 v[250:251], s[18:19], 0, v[130:131]
	s_mov_b32 m0, s37
	s_nop 0
	global_load_lds_dwordx4 v[250:251], off
	s_waitcnt vmcnt(8)
	s_waitcnt lgkmcnt(0)
	s_barrier
; #define PG8_STAGE(bufoff, gbase, voff) do { _Pragma("unroll") for (int _i = 0; _i < 2; ++_i) \
;         __builtin_amdgcn_global_load_lds((const unsigned*)((const char*)(gbase) + (voff)[_i]), (PG8_LAS unsigned*)(lds + (bufoff) + ldsw + _i * 8192), 16, 0, 0); } while (0)
; #define PG8_LDA(dst, b, h) do { _Pragma("unroll") for (int m = 0; m < 4; ++m) _Pragma("unroll") for (int k = 0; k < 2; ++k) dst[m][k] = *(const PG8_LAS bf16x8*)(lds + PG8_SA(b, h) + aoff + m * 2048 + k * 1024); } while (0)
; #define PG8_MMA(ai, bj, At, Bt) do { __builtin_amdgcn_s_setprio(1); _Pragma("unroll") for (int m = 0; m < 4; ++m) _Pragma("unroll") for (int n = 0; n < 2; ++n) _Pragma("unroll") for (int k = 0; k < 2; ++k) \
;         acc[ai][bj][m][n] = __builtin_amdgcn_mfma_f32_16x16x32_bf16(Bt[n][k], At[m][k], acc[ai][bj][m][n], 0, 0, 0); __builtin_amdgcn_s_setprio(0); } while (0)
; #define PG8_WAIT_V(n) asm volatile("s_waitcnt vmcnt(" #n ")" ::: "memory")
; #define PG8_WAIT_L(n) asm volatile("s_waitcnt lgkmcnt(" #n ")" ::: "memory")
; #define PG8_BAR __builtin_amdgcn_s_barrier()
; #define PG8_SCHED __builtin_amdgcn_sched_barrier(0)
;     ...
;         for (int t = 0; t < nt; t += 2) {
;     ...
;             PG8_WAIT_V(8); PG8_WAIT_L(0); PG8_BAR; PG8_MMA(0, 0, At, B0); PG8_MMA(0, 1, At, B1); PG8_BAR; PG8_SCHED;
;             PG8_LDA(At, 1, 1); PG8_STAGE(PG8_SB(1, 0), b3, voffB); PG8_STAGE(PG8_SB(1, 1), b3 + hstepB, voffB); PG8_STAGE(PG8_SA(1, 0), a3, voffA);
;             PG8_WAIT_V(8); PG8_WAIT_L(0); PG8_BAR; PG8_MMA(1, 0, At, B0); PG8_MMA(1, 1, At, B1); PG8_BAR; PG8_SCHED;
	s_setprio 1
	s_waitcnt lgkmcnt(0)
	v_mfma_f32_16x16x32_bf16 v[124:127], v[162:165], v[194:197], v[124:127]
	v_mfma_f32_16x16x32_bf16 v[120:123], v[170:173], v[194:197], v[120:123]
	v_mfma_f32_16x16x32_bf16 v[116:119], v[162:165], v[202:205], v[116:119]
	v_mfma_f32_16x16x32_bf16 v[108:111], v[170:173], v[202:205], v[108:111]
	v_mfma_f32_16x16x32_bf16 v[100:103], v[162:165], v[222:225], v[100:103]
	v_mfma_f32_16x16x32_bf16 v[92:95], v[170:173], v[222:225], v[92:95]
	v_mfma_f32_16x16x32_bf16 v[84:87], v[162:165], v[242:245], v[84:87]
	v_mfma_f32_16x16x32_bf16 v[76:79], v[170:173], v[242:245], v[76:79]
	v_mfma_f32_16x16x32_bf16 v[124:127], v[166:169], v[198:201], v[124:127]
	v_mfma_f32_16x16x32_bf16 v[120:123], v[174:177], v[198:201], v[120:123]
	v_mfma_f32_16x16x32_bf16 v[116:119], v[166:169], v[218:221], v[116:119]
	v_mfma_f32_16x16x32_bf16 v[108:111], v[174:177], v[218:221], v[108:111]
	v_mfma_f32_16x16x32_bf16 v[100:103], v[166:169], v[238:241], v[100:103]
	v_mfma_f32_16x16x32_bf16 v[92:95], v[174:177], v[238:241], v[92:95]
	v_mfma_f32_16x16x32_bf16 v[84:87], v[166:169], v[246:249], v[84:87]
	v_mfma_f32_16x16x32_bf16 v[76:79], v[174:177], v[246:249], v[76:79]
	s_setprio 0
	s_setprio 1
	v_mfma_f32_16x16x32_bf16 v[112:115], v[178:181], v[194:197], v[112:115]
	v_mfma_f32_16x16x32_bf16 v[104:107], v[186:189], v[194:197], v[104:107]
	v_mfma_f32_16x16x32_bf16 v[96:99], v[178:181], v[202:205], v[96:99]
	v_mfma_f32_16x16x32_bf16 v[88:91], v[186:189], v[202:205], v[88:91]
	v_mfma_f32_16x16x32_bf16 v[80:83], v[178:181], v[222:225], v[80:83]
	v_mfma_f32_16x16x32_bf16 v[72:75], v[186:189], v[222:225], v[72:75]
	v_mfma_f32_16x16x32_bf16 v[68:71], v[178:181], v[242:245], v[68:71]
	v_mfma_f32_16x16x32_bf16 v[64:67], v[186:189], v[242:245], v[64:67]
	v_mfma_f32_16x16x32_bf16 v[112:115], v[182:185], v[198:201], v[112:115]
	v_mfma_f32_16x16x32_bf16 v[104:107], v[190:193], v[198:201], v[104:107]
	v_mfma_f32_16x16x32_bf16 v[96:99], v[182:185], v[218:221], v[96:99]
	v_mfma_f32_16x16x32_bf16 v[88:91], v[190:193], v[218:221], v[88:91]
	v_mfma_f32_16x16x32_bf16 v[80:83], v[182:185], v[238:241], v[80:83]
	v_mfma_f32_16x16x32_bf16 v[72:75], v[190:193], v[238:241], v[72:75]
	v_mfma_f32_16x16x32_bf16 v[68:71], v[182:185], v[246:249], v[68:71]
	v_mfma_f32_16x16x32_bf16 v[64:67], v[190:193], v[246:249], v[64:67]
	s_setprio 0
	s_barrier
	s_mov_b32 m0, s55
	v_lshl_add_u64 v[140:141], v[140:141], 0, s[66:67]
	ds_read_b128 v[194:197], v160 offset:49152
	ds_read_b128 v[198:201], v160 offset:50176
	ds_read_b128 v[202:205], v160 offset:51200
	ds_read_b128 v[218:221], v160 offset:52224
	ds_read_b128 v[222:225], v160 offset:53248
	ds_read_b128 v[238:241], v160 offset:54272
	ds_read_b128 v[242:245], v160 offset:55296
	ds_read_b128 v[246:249], v160 offset:56320
	global_load_lds_dwordx4 v[140:141], off
	v_lshl_add_u64 v[140:141], v[206:207], 0, s[66:67]
	s_mov_b32 m0, s54
	s_nop 0
	global_load_lds_dwordx4 v[140:141], off
	v_lshl_add_u64 v[140:141], s[16:17], 0, v[134:135]
	s_mov_b32 m0, s63
	s_nop 0
	global_load_lds_dwordx4 v[140:141], off
	v_lshl_add_u64 v[140:141], s[16:17], 0, v[132:133]
	s_mov_b32 m0, s62
	s_nop 0
	global_load_lds_dwordx4 v[140:141], off
	v_lshl_add_u64 v[140:141], s[14:15], 0, v[128:129]
	s_mov_b32 m0, s40
	s_nop 0
	global_load_lds_dwordx4 v[140:141], off
	v_lshl_add_u64 v[140:141], s[14:15], 0, v[130:131]
	s_mov_b32 m0, s41
	s_nop 0
	global_load_lds_dwordx4 v[140:141], off
	s_waitcnt vmcnt(8)
	s_waitcnt lgkmcnt(0)
	s_barrier
	s_setprio 1
	s_waitcnt lgkmcnt(0)
	v_mfma_f32_16x16x32_bf16 v[60:63], v[162:165], v[194:197], v[60:63]
	v_mfma_f32_16x16x32_bf16 v[56:59], v[170:173], v[194:197], v[56:59]
	v_mfma_f32_16x16x32_bf16 v[52:55], v[162:165], v[202:205], v[52:55]
	v_mfma_f32_16x16x32_bf16 v[44:47], v[170:173], v[202:205], v[44:47]
	v_mfma_f32_16x16x32_bf16 v[36:39], v[162:165], v[222:225], v[36:39]
	v_mfma_f32_16x16x32_bf16 v[28:31], v[170:173], v[222:225], v[28:31]
	v_mfma_f32_16x16x32_bf16 v[20:23], v[162:165], v[242:245], v[20:23]
	v_mfma_f32_16x16x32_bf16 v[12:15], v[170:173], v[242:245], v[12:15]
	v_mfma_f32_16x16x32_bf16 v[60:63], v[166:169], v[198:201], v[60:63]
	v_mfma_f32_16x16x32_bf16 v[56:59], v[174:177], v[198:201], v[56:59]
	v_mfma_f32_16x16x32_bf16 v[52:55], v[166:169], v[218:221], v[52:55]
	v_mfma_f32_16x16x32_bf16 v[44:47], v[174:177], v[218:221], v[44:47]
	v_mfma_f32_16x16x32_bf16 v[36:39], v[166:169], v[238:241], v[36:39]
	v_mfma_f32_16x16x32_bf16 v[28:31], v[174:177], v[238:241], v[28:31]
	v_mfma_f32_16x16x32_bf16 v[20:23], v[166:169], v[246:249], v[20:23]
	v_mfma_f32_16x16x32_bf16 v[12:15], v[174:177], v[246:249], v[12:15]
	s_setprio 0
	s_setprio 1
	v_mfma_f32_16x16x32_bf16 v[48:51], v[178:181], v[194:197], v[48:51]
	v_mfma_f32_16x16x32_bf16 v[40:43], v[186:189], v[194:197], v[40:43]
	v_mfma_f32_16x16x32_bf16 v[32:35], v[178:181], v[202:205], v[32:35]
	v_mfma_f32_16x16x32_bf16 v[24:27], v[186:189], v[202:205], v[24:27]
	v_mfma_f32_16x16x32_bf16 v[16:19], v[178:181], v[222:225], v[16:19]
	v_mfma_f32_16x16x32_bf16 v[8:11], v[186:189], v[222:225], v[8:11]
	v_mfma_f32_16x16x32_bf16 v[4:7], v[178:181], v[242:245], v[4:7]
	v_mfma_f32_16x16x32_bf16 v[0:3], v[186:189], v[242:245], v[0:3]
	v_mfma_f32_16x16x32_bf16 v[48:51], v[182:185], v[198:201], v[48:51]
	v_mfma_f32_16x16x32_bf16 v[40:43], v[190:193], v[198:201], v[40:43]
	v_mfma_f32_16x16x32_bf16 v[32:35], v[182:185], v[218:221], v[32:35]
	v_mfma_f32_16x16x32_bf16 v[24:27], v[190:193], v[218:221], v[24:27]
	v_mfma_f32_16x16x32_bf16 v[16:19], v[182:185], v[238:241], v[16:19]
	v_mfma_f32_16x16x32_bf16 v[8:11], v[190:193], v[238:241], v[8:11]
	v_mfma_f32_16x16x32_bf16 v[4:7], v[182:185], v[246:249], v[4:7]
	v_mfma_f32_16x16x32_bf16 v[0:3], v[190:193], v[246:249], v[0:3]
	s_setprio 0
	s_barrier
	s_andn2_b64 vcc, exec, s[12:13]
	s_mov_b64 s[16:17], -1
	s_mov_b64 s[12:13], 0
	s_movk_i32 s14, 0x100
	s_cbranch_vccz .LBB0_785
	s_branch .Lpeel_exit_785

; #define PG8_BAR __builtin_amdgcn_s_barrier()
;     ...
;         }
;         if (wr == 0) PG8_BAR;
.Lpeel_exit_785:
	s_and_b64 vcc, exec, s[4:5]
	s_cbranch_vccz .LBB0_788
	s_barrier
